# cvhost column variant with nt hint on the hosted weight loads and bf16 store
# baseline (speedup 1.0000x reference)
; #define GAS __attribute__((address_space(1)))
; __device__ __forceinline__ unsigned cvt_pk_bf16(float lo, float hi) { unsigned r; asm volatile("v_cvt_pk_bf16_f32 %0, %1, %2" : "=v"(r) : "v"(lo), "v"(hi)); return r; }
; template <int NB>
; __device__ __forceinline__ void p0_batch(int it0, int stride, int lane, const P0Ptrs& a) {
;     ...
;         if (d[q].dst) {
; #pragma unroll
;             for (int e = 0; e < 4; ++e) { u32x4 o; o.x = cvt_pk_bf16(v[q][0][e], v[q][1][e]); o.y = cvt_pk_bf16(v[q][2][e], v[q][3][e]); o.z = cvt_pk_bf16(v[q][4][e], v[q][5][e]); o.w = cvt_pk_bf16(v[q][6][e], v[q][7][e]);
;                 *(GAS u32x4*)(d[q].dst + (size_t)e * d[q].ldt) = o; } }
.Lcv_nomul:
	v_and_b32_e32 v83, 7, v0
	v_bfe_u32 v82, v0, 3, 3
	s_lshl_b32 s98, s91, 2
	v_cvt_pk_bf16_f32 v76, v237, v246
	v_cvt_pk_bf16_f32 v77, v250, v251
	v_mul_u32_u24_e32 v81, s98, v83
	v_cvt_pk_bf16_f32 v78, v252, v253
	v_cvt_pk_bf16_f32 v79, v254, v255
	v_lshl_add_u32 v81, v82, 4, v81
	s_nop 0
	global_store_dwordx4 v81, v[76:79], s[92:93] nt
	s_add_u32 s92, s92, s91
	s_addc_u32 s93, s93, 0

; template <int NB>
; __device__ __forceinline__ void p0_batch(int it0, int stride, int lane, const P0Ptrs& a) {
;     ...
;     for (int q = 0; q < NB; ++q) { const bool ok = it0 < NFAST / 4; d[q] = p0_desc(p0_super(ok ? it0 : 0, q), lane, a); if (!ok) d[q].dst = nullptr;
; #pragma unroll
;         for (int i = 0; i < 8; ++i) v[q][i] = __builtin_nontemporal_load((const f32x4*)(d[q].src + (size_t)i * d[q].nsrc));
;         const float* kp = d[q].ks ? d[q].ks : a.ffn_g;
;         s0[q] = *(const f32x4*)(kp); s1[q] = *(const f32x4*)(kp + 4); }
.Lcv_loads:
	v_and_b32_e32 v83, 7, v0
	v_bfe_u32 v82, v0, 3, 3
	s_lshl_b32 s98, s90, 3
	v_lshlrev_b32_e32 v83, 4, v83
	v_mad_u32_u24 v80, v82, s98, v83
	s_mov_b64 s[98:99], s[88:89]
	global_load_dword v237, v80, s[98:99] nt
	s_add_u32 s98, s98, s90
	s_addc_u32 s99, s99, 0
	global_load_dword v246, v80, s[98:99] nt
	s_add_u32 s98, s98, s90
	s_addc_u32 s99, s99, 0
	global_load_dword v250, v80, s[98:99] nt
	s_add_u32 s98, s98, s90
	s_addc_u32 s99, s99, 0
	global_load_dword v251, v80, s[98:99] nt
	s_add_u32 s98, s98, s90
	s_addc_u32 s99, s99, 0
	global_load_dword v252, v80, s[98:99] nt
	s_add_u32 s98, s98, s90
	s_addc_u32 s99, s99, 0
	global_load_dword v253, v80, s[98:99] nt
	s_add_u32 s98, s98, s90
	s_addc_u32 s99, s99, 0
	global_load_dword v254, v80, s[98:99] nt
	s_add_u32 s98, s98, s90
	s_addc_u32 s99, s99, 0
	global_load_dword v255, v80, s[98:99] nt
	s_add_u32 s88, s88, 4
	s_addc_u32 s89, s89, 0
	s_and_b32 s98, s87, 3
	s_cmp_lg_u32 s98, 3
	s_cbranch_scc1 .Lcv_inc
	s_cmp_gt_u32 s87, 18
	s_cbranch_scc1 .Lcv_inc
	s_add_i32 s99, s32, 1
	s_movk_i32 s98, 0x78
	s_cmp_lt_u32 s99, 7
	s_cselect_b32 s98, 0x60, s98
	s_cmp_eq_u32 s99, 0
	s_cselect_b32 s98, 0x50, s98
	s_cselect_b32 s99, 0, 0x58
	s_load_dwordx2 s[88:89], s[100:101], s98
	s_cmp_eq_u32 s99, 0
	s_cbranch_scc0 .Lcv_s1b_s
	s_bfe_u32 s99, s2, 0x50003
	s_cmp_lt_u32 s99, 16
	s_cselect_b32 s99, 64, 0x48
